# P1 epilogue stores write-through (sc1) on top of v33
# baseline (speedup 1.0000x reference)
.LBB0_118:
	s_cmp_lt_i32 s18, 2
	s_cselect_b64 vcc, -1, 0
	v_cndmask_b32_e32 v172, 1.0, v193, vcc
	v_pk_mul_f32 v[126:127], v[172:173], v[126:127] op_sel_hi:[0,1]
	v_pk_mul_f32 v[124:125], v[172:173], v[124:125] op_sel_hi:[0,1]
	v_pk_mul_f32 v[208:209], v[172:173], v[122:123] op_sel_hi:[0,1]
	v_pk_mul_f32 v[122:123], v[172:173], v[120:121] op_sel_hi:[0,1]
	v_cvt_pk_bf16_f32 v120, v124, v125
	v_cvt_pk_bf16_f32 v121, v126, v127
	v_cvt_pk_bf16_f32 v122, v122, v123
	v_cvt_pk_bf16_f32 v123, v208, v209
	s_and_b64 vcc, exec, s[6:7]
	global_store_dwordx4 v[178:179], v[120:123], off sc1
	s_cbranch_vccnz .LBB0_122
	s_nop 0
	v_and_b32_e32 v121, 64, v192
	v_xor_b32_e32 v120, 16, v192
	v_add_u32_e32 v121, 64, v121
	v_cmp_lt_i32_e32 vcc, v120, v121
	s_nop 1
	v_cndmask_b32_e32 v120, v192, v120, vcc
	v_lshlrev_b32_e32 v125, 2, v120
	ds_bpermute_b32 v122, v125, v116
	ds_bpermute_b32 v120, v125, v112
	ds_bpermute_b32 v123, v125, v117
	ds_bpermute_b32 v121, v125, v113
	ds_bpermute_b32 v126, v125, v118
	ds_bpermute_b32 v124, v125, v114
	ds_bpermute_b32 v127, v125, v119
	ds_bpermute_b32 v125, v125, v115
	s_and_saveexec_b64 s[8:9], s[14:15]
	s_cbranch_execz .LBB0_121
	s_waitcnt lgkmcnt(0)
	v_mul_f32_e32 v127, v164, v127
	s_waitcnt vmcnt(0)
	v_mov_b32_e32 v178, v136
	v_mov_b32_e32 v179, v138
	v_mov_b32_e32 v138, v137
	v_mov_b32_e32 v136, v119
	v_mov_b32_e32 v137, v143
	v_mov_b32_e32 v143, v127
	v_mul_f32_e32 v126, v164, v126
	v_pk_mul_f32 v[136:137], v[136:137], v[142:143]
	v_pk_mul_f32 v[122:123], v[164:165], v[122:123]
	v_mul_f32_e32 v118, v118, v140
	v_mul_f32_e32 v126, v141, v126
	v_mov_b32_e32 v119, v136
	v_mov_b32_e32 v127, v137
	v_mul_f32_e32 v125, v164, v125
	v_pk_mul_f32 v[122:123], v[138:139], v[122:123]
	v_pk_add_f32 v[118:119], v[118:119], v[126:127]
	v_mov_b32_e32 v126, v115
	v_mov_b32_e32 v127, v131
	v_mov_b32_e32 v131, v125
	v_pk_fma_f32 v[116:117], v[116:117], v[178:179], v[122:123]
	v_mov_b32_e32 v123, v134
	v_pk_mul_f32 v[120:121], v[164:165], v[120:121]
	v_mov_b32_e32 v134, v133
	v_mul_f32_e32 v124, v164, v124
	v_pk_mul_f32 v[126:127], v[126:127], v[130:131]
	v_mov_b32_e32 v122, v132
	v_pk_mul_f32 v[120:121], v[134:135], v[120:121]
	v_mul_f32_e32 v114, v114, v128
	v_mul_f32_e32 v124, v129, v124
	v_mov_b32_e32 v115, v126
	v_mov_b32_e32 v125, v127
	v_pk_fma_f32 v[112:113], v[112:113], v[122:123], v[120:121]
	v_pk_add_f32 v[114:115], v[114:115], v[124:125]

.LBB0_126:
	v_mov_b32_e32 v173, v172
	v_mov_b32_e32 v122, v172
	v_mov_b32_e32 v123, v172
	v_pk_mul_f32 v[118:119], v[122:123], v[118:119]
	v_pk_mul_f32 v[116:117], v[172:173], v[116:117]
	v_pk_mul_f32 v[122:123], v[122:123], v[114:115]
	v_pk_mul_f32 v[114:115], v[172:173], v[112:113]
	s_waitcnt vmcnt(0)
	v_or_b32_e32 v134, 16, v206
	v_cvt_pk_bf16_f32 v112, v116, v117
	v_cvt_pk_bf16_f32 v113, v118, v119
	v_cvt_pk_bf16_f32 v114, v114, v115
	v_cvt_pk_bf16_f32 v115, v122, v123
	s_and_b64 vcc, exec, s[6:7]
	v_cmp_gt_i32_e64 s[10:11], s53, v134
	global_store_dwordx4 v[120:121], v[112:115], off sc1
	s_cbranch_vccnz .LBB0_128
	s_nop 0
	v_cndmask_b32_e64 v112, v194, v195, s[10:11]
	v_and_b32_e32 v112, v112, v134
	v_lshlrev_b32_e32 v112, 6, v112
	global_load_dwordx4 v[120:123], v112, s[16:17]
	global_load_dwordx4 v[124:127], v112, s[16:17] offset:16
	global_load_dwordx4 v[116:119], v112, s[16:17] offset:32
	s_nop 0
	global_load_dwordx4 v[112:115], v112, s[16:17] offset:48
	s_branch .LBB0_129

.LBB0_139:
	v_mov_b32_e32 v134, v172
	s_waitcnt lgkmcnt(2)
	v_mov_b32_e32 v135, v172
	v_pk_mul_f32 v[110:111], v[134:135], v[110:111]
	v_pk_mul_f32 v[108:109], v[172:173], v[108:109]
	v_pk_mul_f32 v[134:135], v[134:135], v[106:107]
	v_pk_mul_f32 v[106:107], v[172:173], v[104:105]
	v_cvt_pk_bf16_f32 v104, v108, v109
	v_cvt_pk_bf16_f32 v105, v110, v111
	v_cvt_pk_bf16_f32 v106, v106, v107
	v_cvt_pk_bf16_f32 v107, v134, v135
	s_and_b64 vcc, exec, s[6:7]
	global_store_dwordx4 v[132:133], v[104:107], off sc1
	s_cbranch_vccz .LBB0_145
	s_and_b64 vcc, exec, s[8:9]
	s_mov_b64 s[12:13], -1
	s_cbranch_vccz .LBB0_148

.LBB0_143:
	s_waitcnt lgkmcnt(7)
	v_mov_b32_e32 v106, v172
	s_waitcnt lgkmcnt(5)
	v_mov_b32_e32 v107, v172
	v_pk_mul_f32 v[102:103], v[106:107], v[102:103]
	v_pk_mul_f32 v[100:101], v[172:173], v[100:101]
	v_pk_mul_f32 v[106:107], v[106:107], v[98:99]
	v_pk_mul_f32 v[98:99], v[172:173], v[96:97]
	s_waitcnt vmcnt(2)
	v_or_b32_e32 v118, 32, v206
	v_cvt_pk_bf16_f32 v96, v100, v101
	v_cvt_pk_bf16_f32 v97, v102, v103
	v_cvt_pk_bf16_f32 v98, v98, v99
	v_cvt_pk_bf16_f32 v99, v106, v107
	s_and_b64 vcc, exec, s[6:7]
	v_cmp_gt_i32_e64 s[12:13], s53, v118
	s_waitcnt lgkmcnt(4)
	global_store_dwordx4 v[104:105], v[96:99], off sc1
	s_cbranch_vccnz .LBB0_149
	s_nop 0
	v_cndmask_b32_e64 v96, v198, v199, s[12:13]
	v_and_b32_e32 v96, v96, v118
	v_lshlrev_b32_e32 v96, 6, v96
	global_load_dwordx4 v[104:107], v96, s[16:17]
	s_waitcnt lgkmcnt(0)
	global_load_dwordx4 v[108:111], v96, s[16:17] offset:16
	global_load_dwordx4 v[100:103], v96, s[16:17] offset:32
	s_nop 0
	global_load_dwordx4 v[96:99], v96, s[16:17] offset:48
	s_and_b64 vcc, exec, s[10:11]
	s_waitcnt vmcnt(6)
	v_mov_b64_e32 v[112:113], 0
	s_cbranch_vccz .LBB0_150
	s_branch .LBB0_151

.LBB0_159:
	v_mov_b32_e32 v118, v172
	s_waitcnt lgkmcnt(2)
	v_mov_b32_e32 v119, v172
	v_pk_mul_f32 v[94:95], v[118:119], v[94:95]
	v_pk_mul_f32 v[92:93], v[172:173], v[92:93]
	v_pk_mul_f32 v[118:119], v[118:119], v[90:91]
	v_pk_mul_f32 v[90:91], v[172:173], v[88:89]
	v_cvt_pk_bf16_f32 v88, v92, v93
	v_cvt_pk_bf16_f32 v89, v94, v95
	v_cvt_pk_bf16_f32 v90, v90, v91
	v_cvt_pk_bf16_f32 v91, v118, v119
	s_and_b64 vcc, exec, s[6:7]
	global_store_dwordx4 v[116:117], v[88:91], off sc1
	s_cbranch_vccz .LBB0_165
	s_and_b64 vcc, exec, s[8:9]
	s_mov_b64 s[12:13], -1
	s_cbranch_vccz .LBB0_168

.LBB0_163:
	s_waitcnt lgkmcnt(7)
	v_mov_b32_e32 v90, v172
	s_waitcnt lgkmcnt(5)
	v_mov_b32_e32 v91, v172
	v_pk_mul_f32 v[86:87], v[90:91], v[86:87]
	v_pk_mul_f32 v[84:85], v[172:173], v[84:85]
	v_pk_mul_f32 v[90:91], v[90:91], v[82:83]
	v_pk_mul_f32 v[82:83], v[172:173], v[80:81]
	s_waitcnt vmcnt(2)
	v_or_b32_e32 v102, 48, v206
	v_cvt_pk_bf16_f32 v80, v84, v85
	v_cvt_pk_bf16_f32 v81, v86, v87
	v_cvt_pk_bf16_f32 v82, v82, v83
	v_cvt_pk_bf16_f32 v83, v90, v91
	s_and_b64 vcc, exec, s[6:7]
	v_cmp_gt_i32_e64 s[12:13], s53, v102
	s_waitcnt lgkmcnt(4)
	global_store_dwordx4 v[88:89], v[80:83], off sc1
	s_cbranch_vccnz .LBB0_169
	s_nop 0
	v_cndmask_b32_e64 v80, v202, v203, s[12:13]
	v_and_b32_e32 v80, v80, v102
	v_lshlrev_b32_e32 v80, 6, v80
	global_load_dwordx4 v[88:91], v80, s[16:17]
	s_waitcnt lgkmcnt(0)
	global_load_dwordx4 v[92:95], v80, s[16:17] offset:16
	global_load_dwordx4 v[84:87], v80, s[16:17] offset:32
	s_nop 0
	global_load_dwordx4 v[80:83], v80, s[16:17] offset:48
	s_and_b64 vcc, exec, s[10:11]
	s_waitcnt vmcnt(6)
	v_mov_b64_e32 v[96:97], 0
	s_cbranch_vccz .LBB0_170
	s_branch .LBB0_171

.LBB0_179:
	v_mov_b32_e32 v102, v172
	s_waitcnt lgkmcnt(2)
	v_mov_b32_e32 v103, v172
	v_pk_mul_f32 v[78:79], v[102:103], v[78:79]
	v_pk_mul_f32 v[76:77], v[172:173], v[76:77]
	v_pk_mul_f32 v[102:103], v[102:103], v[74:75]
	v_pk_mul_f32 v[74:75], v[172:173], v[72:73]
	v_cvt_pk_bf16_f32 v72, v76, v77
	v_cvt_pk_bf16_f32 v73, v78, v79
	v_cvt_pk_bf16_f32 v74, v74, v75
	v_cvt_pk_bf16_f32 v75, v102, v103
	s_and_b64 vcc, exec, s[6:7]
	global_store_dwordx4 v[100:101], v[72:75], off sc1
	s_cbranch_vccz .LBB0_185
	s_and_b64 vcc, exec, s[8:9]
	s_mov_b64 s[12:13], -1
	s_cbranch_vccz .LBB0_188

.LBB0_183:
	s_waitcnt lgkmcnt(7)
	v_mov_b32_e32 v74, v172
	s_waitcnt lgkmcnt(5)
	v_mov_b32_e32 v75, v172
	v_pk_mul_f32 v[70:71], v[74:75], v[70:71]
	v_pk_mul_f32 v[68:69], v[172:173], v[68:69]
	v_pk_mul_f32 v[74:75], v[74:75], v[66:67]
	v_pk_mul_f32 v[66:67], v[172:173], v[64:65]
	v_cvt_pk_bf16_f32 v64, v68, v69
	v_cvt_pk_bf16_f32 v65, v70, v71
	v_cvt_pk_bf16_f32 v66, v66, v67
	v_cvt_pk_bf16_f32 v67, v74, v75
	s_waitcnt vmcnt(2)
	v_add_u32_e32 v86, 0x80, v206
	s_and_b64 vcc, exec, s[6:7]
	v_cmp_gt_i32_e64 s[12:13], s60, v206
	s_waitcnt lgkmcnt(4)
	global_store_dwordx4 v[72:73], v[64:67], off sc1
	s_cbranch_vccnz .LBB0_189
	s_nop 0
	v_cndmask_b32_e64 v64, v184, v185, s[12:13]
	v_and_b32_e32 v64, v64, v86
	v_lshlrev_b32_e32 v64, 6, v64
	global_load_dwordx4 v[72:75], v64, s[16:17]
	s_waitcnt lgkmcnt(0)
	global_load_dwordx4 v[76:79], v64, s[16:17] offset:16
	global_load_dwordx4 v[68:71], v64, s[16:17] offset:32
	s_nop 0
	global_load_dwordx4 v[64:67], v64, s[16:17] offset:48
	s_and_b64 vcc, exec, s[10:11]
	s_waitcnt vmcnt(6)
	v_mov_b64_e32 v[80:81], 0
	s_cbranch_vccz .LBB0_190
	s_branch .LBB0_191

.LBB0_199:
	s_waitcnt lgkmcnt(0)
	v_mov_b32_e32 v88, v172
	v_mov_b32_e32 v89, v172
	v_pk_mul_f32 v[62:63], v[88:89], v[62:63]
	v_pk_mul_f32 v[60:61], v[172:173], v[60:61]
	v_pk_mul_f32 v[88:89], v[88:89], v[58:59]
	v_pk_mul_f32 v[58:59], v[172:173], v[56:57]
	v_cvt_pk_bf16_f32 v56, v60, v61
	v_cvt_pk_bf16_f32 v57, v62, v63
	v_cvt_pk_bf16_f32 v58, v58, v59
	v_cvt_pk_bf16_f32 v59, v88, v89
	s_and_b64 vcc, exec, s[6:7]
	global_store_dwordx4 v[84:85], v[56:59], off sc1
	s_cbranch_vccz .LBB0_205
	s_and_b64 vcc, exec, s[8:9]
	s_mov_b64 s[12:13], -1
	s_cbranch_vccz .LBB0_208

.LBB0_203:
	s_waitcnt lgkmcnt(7)
	v_mov_b32_e32 v58, v172
	s_waitcnt lgkmcnt(5)
	v_mov_b32_e32 v59, v172
	v_pk_mul_f32 v[54:55], v[58:59], v[54:55]
	v_pk_mul_f32 v[52:53], v[172:173], v[52:53]
	v_pk_mul_f32 v[58:59], v[58:59], v[50:51]
	v_pk_mul_f32 v[50:51], v[172:173], v[48:49]
	v_cvt_pk_bf16_f32 v48, v52, v53
	v_cvt_pk_bf16_f32 v49, v54, v55
	v_cvt_pk_bf16_f32 v50, v50, v51
	v_cvt_pk_bf16_f32 v51, v58, v59
	s_waitcnt vmcnt(2)
	v_add_u32_e32 v70, 0x90, v206
	s_and_b64 vcc, exec, s[6:7]
	v_cmp_gt_i32_e64 s[12:13], s61, v206
	s_waitcnt lgkmcnt(4)
	global_store_dwordx4 v[56:57], v[48:51], off sc1
	s_cbranch_vccnz .LBB0_209
	s_nop 0
	v_cndmask_b32_e64 v48, v194, v195, s[12:13]
	v_and_b32_e32 v48, v48, v70
	v_lshlrev_b32_e32 v48, 6, v48
	global_load_dwordx4 v[56:59], v48, s[16:17]
	s_waitcnt lgkmcnt(0)
	global_load_dwordx4 v[60:63], v48, s[16:17] offset:16
	global_load_dwordx4 v[52:55], v48, s[16:17] offset:32
	s_nop 0
	global_load_dwordx4 v[48:51], v48, s[16:17] offset:48
	s_and_b64 vcc, exec, s[10:11]
	s_waitcnt vmcnt(6)
	v_mov_b64_e32 v[64:65], 0
	s_cbranch_vccz .LBB0_210
	s_branch .LBB0_211

.LBB0_219:
	v_mov_b32_e32 v70, v172
	s_waitcnt lgkmcnt(2)
	v_mov_b32_e32 v71, v172
	v_pk_mul_f32 v[46:47], v[70:71], v[46:47]
	v_pk_mul_f32 v[44:45], v[172:173], v[44:45]
	v_pk_mul_f32 v[70:71], v[70:71], v[42:43]
	v_pk_mul_f32 v[42:43], v[172:173], v[40:41]
	v_cvt_pk_bf16_f32 v40, v44, v45
	v_cvt_pk_bf16_f32 v41, v46, v47
	v_cvt_pk_bf16_f32 v42, v42, v43
	v_cvt_pk_bf16_f32 v43, v70, v71
	s_and_b64 vcc, exec, s[6:7]
	global_store_dwordx4 v[68:69], v[40:43], off sc1
	s_cbranch_vccz .LBB0_225
	s_and_b64 vcc, exec, s[8:9]
	s_mov_b64 s[12:13], -1
	s_cbranch_vccz .LBB0_228

.LBB0_223:
	s_waitcnt lgkmcnt(7)
	v_mov_b32_e32 v42, v172
	s_waitcnt lgkmcnt(5)
	v_mov_b32_e32 v43, v172
	v_pk_mul_f32 v[38:39], v[42:43], v[38:39]
	v_pk_mul_f32 v[36:37], v[172:173], v[36:37]
	v_pk_mul_f32 v[42:43], v[42:43], v[34:35]
	v_pk_mul_f32 v[34:35], v[172:173], v[32:33]
	v_cvt_pk_bf16_f32 v32, v36, v37
	v_cvt_pk_bf16_f32 v33, v38, v39
	v_cvt_pk_bf16_f32 v34, v34, v35
	v_cvt_pk_bf16_f32 v35, v42, v43
	s_waitcnt vmcnt(2)
	v_add_u32_e32 v54, 0xa0, v206
	s_and_b64 vcc, exec, s[6:7]
	v_cmp_gt_i32_e64 s[12:13], s62, v206
	s_waitcnt lgkmcnt(4)
	global_store_dwordx4 v[40:41], v[32:35], off sc1
	s_cbranch_vccnz .LBB0_229
	s_nop 0
	v_cndmask_b32_e64 v32, v198, v199, s[12:13]
	v_and_b32_e32 v32, v32, v54
	v_lshlrev_b32_e32 v32, 6, v32
	global_load_dwordx4 v[40:43], v32, s[16:17]
	s_waitcnt lgkmcnt(0)
	global_load_dwordx4 v[44:47], v32, s[16:17] offset:16
	global_load_dwordx4 v[36:39], v32, s[16:17] offset:32
	s_nop 0
	global_load_dwordx4 v[32:35], v32, s[16:17] offset:48
	s_and_b64 vcc, exec, s[10:11]
	s_waitcnt vmcnt(6)
	v_mov_b64_e32 v[48:49], 0
	s_cbranch_vccz .LBB0_230
	s_branch .LBB0_231

.LBB0_239:
	v_mov_b32_e32 v54, v172
	s_waitcnt lgkmcnt(2)
	v_mov_b32_e32 v55, v172
	v_pk_mul_f32 v[30:31], v[54:55], v[30:31]
	v_pk_mul_f32 v[28:29], v[172:173], v[28:29]
	v_pk_mul_f32 v[54:55], v[54:55], v[26:27]
	v_pk_mul_f32 v[26:27], v[172:173], v[24:25]
	v_cvt_pk_bf16_f32 v24, v28, v29
	v_cvt_pk_bf16_f32 v25, v30, v31
	v_cvt_pk_bf16_f32 v26, v26, v27
	v_cvt_pk_bf16_f32 v27, v54, v55
	s_and_b64 vcc, exec, s[6:7]
	global_store_dwordx4 v[52:53], v[24:27], off sc1
	s_cbranch_vccz .LBB0_245
	s_and_b64 vcc, exec, s[8:9]
	s_mov_b64 s[12:13], -1
	s_cbranch_vccz .LBB0_248

.LBB0_243:
	s_waitcnt lgkmcnt(7)
	v_mov_b32_e32 v26, v172
	s_waitcnt lgkmcnt(5)
	v_mov_b32_e32 v27, v172
	v_pk_mul_f32 v[22:23], v[26:27], v[22:23]
	v_pk_mul_f32 v[20:21], v[172:173], v[20:21]
	v_pk_mul_f32 v[26:27], v[26:27], v[18:19]
	v_pk_mul_f32 v[18:19], v[172:173], v[16:17]
	v_cvt_pk_bf16_f32 v16, v20, v21
	v_cvt_pk_bf16_f32 v17, v22, v23
	v_cvt_pk_bf16_f32 v18, v18, v19
	v_cvt_pk_bf16_f32 v19, v26, v27
	s_waitcnt vmcnt(2)
	v_add_u32_e32 v38, 0xb0, v206
	s_and_b64 vcc, exec, s[6:7]
	v_cmp_gt_i32_e64 s[12:13], s63, v206
	s_waitcnt lgkmcnt(4)
	global_store_dwordx4 v[24:25], v[16:19], off sc1
	s_cbranch_vccnz .LBB0_249
	s_nop 0
	v_cndmask_b32_e64 v16, v202, v203, s[12:13]
	v_and_b32_e32 v16, v16, v38
	v_lshlrev_b32_e32 v16, 6, v16
	global_load_dwordx4 v[24:27], v16, s[16:17]
	s_waitcnt lgkmcnt(0)
	global_load_dwordx4 v[28:31], v16, s[16:17] offset:16
	global_load_dwordx4 v[20:23], v16, s[16:17] offset:32
	s_nop 0
	global_load_dwordx4 v[16:19], v16, s[16:17] offset:48
	s_and_b64 vcc, exec, s[10:11]
	s_waitcnt vmcnt(6)
	v_mov_b64_e32 v[32:33], 0
	s_cbranch_vccz .LBB0_250
	s_branch .LBB0_251

.LBB0_259:
	v_mov_b32_e32 v38, v172
	s_waitcnt lgkmcnt(2)
	v_mov_b32_e32 v39, v172
	v_pk_mul_f32 v[14:15], v[38:39], v[14:15]
	v_pk_mul_f32 v[12:13], v[172:173], v[12:13]
	v_pk_mul_f32 v[38:39], v[38:39], v[10:11]
	v_pk_mul_f32 v[10:11], v[172:173], v[8:9]
	v_cvt_pk_bf16_f32 v8, v12, v13
	v_cvt_pk_bf16_f32 v9, v14, v15
	v_cvt_pk_bf16_f32 v10, v10, v11
	v_cvt_pk_bf16_f32 v11, v38, v39
	s_and_b64 vcc, exec, s[6:7]
	global_store_dwordx4 v[36:37], v[8:11], off sc1
	s_cbranch_vccz .LBB0_266
	s_and_b64 vcc, exec, s[8:9]
	s_mov_b64 s[6:7], -1
	s_cbranch_vccz .LBB0_269

.LBB0_263:
	s_waitcnt lgkmcnt(7)
	v_mov_b32_e32 v10, v172
	s_waitcnt lgkmcnt(5)
	v_mov_b32_e32 v11, v172
	v_pk_mul_f32 v[6:7], v[10:11], v[6:7]
	v_pk_mul_f32 v[4:5], v[172:173], v[4:5]
	v_pk_mul_f32 v[2:3], v[10:11], v[2:3]
	v_pk_mul_f32 v[0:1], v[172:173], v[0:1]
	v_cvt_pk_bf16_f32 v4, v4, v5
	v_cvt_pk_bf16_f32 v5, v6, v7
	v_cvt_pk_bf16_f32 v6, v0, v1
	v_cvt_pk_bf16_f32 v7, v2, v3
	s_andn2_b64 vcc, exec, s[4:5]
	s_mov_b64 s[4:5], -1
	s_waitcnt lgkmcnt(4)
	global_store_dwordx4 v[8:9], v[4:7], off sc1
	s_cbranch_vccnz .LBB0_94
	s_andn2_b64 vcc, exec, s[22:23]
	s_cbranch_vccnz .LBB0_93
	s_barrier
	s_branch .LBB0_93
